# previous combination plus a second attention code path without the causal-mask compares/selects for key blocks that lie entirely before the wave's queries
# speedup vs baseline: 1.0256x; 1.0070x over previous
; #define LAS __attribute__((address_space(3)))
; __device__ __forceinline__ void attn_unit(LAS unsigned char* lds, const bf16_t* Qm, const bf16_t* Km, const bf16_t* VT, const bf16_t* GBm, bf16_t* YB, int b, int hp, int qb) {
;     ...
;         if (k0 < qw + 15 && !__all(Rs == 0.f)) {
;             f32x4 s[4];
; #pragma unroll
;             for (int rb = 0; rb < 4; ++rb) {
;                 const int c = rb >> 1, e = rb & 1;
;                 const int kl = 32 * c + (fr >> 2) * 8 + e * 4 + (fr & 3);
;                 s[rb] = (f32x4){0.f, 0.f, 0.f, 0.f};
; #pragma unroll
;                 for (int ks = 0; ks < 4; ++ks) {
;                     const bf16x8 a = *(const LAS bf16x8*)(KL + kl * 272 + (ks * 32 + fq * 8) * 2);
;                     s[rb] = __builtin_amdgcn_mfma_f32_16x16x32_bf16(a, qf[ks], s[rb], 0, 0, 0);
;                 }
;             }
;             const int qi = qw + fr;
;             float be[2][8], om[2][8];
; #pragma unroll
;             for (int c = 0; c < 2; ++c)
; #pragma unroll
;                 for (int i = 0; i < 8; ++i) {
;                     const float z = s[2 * c + (i >> 2)][i & 3];
;                     const int key = k0 + 32 * c + 8 * fq + i;
;                     const float e = __builtin_amdgcn_exp2f(-fabsf(z));
;                     const float r = __builtin_amdgcn_rcpf(1.0f + e);
;                     const bool pos = z >= 0.f, valid = key < qi;
;                     be[c][i] = valid ? (pos ? r : e * r) : 0.f;
;                     om[c][i] = valid ? (pos ? e * r : r) : 1.f;
.LBB0_519:
	s_add_i32 s12, s56, 64
	v_cmp_lt_u32_e32 vcc, s12, v109
	s_and_saveexec_b64 s[58:59], vcc
	s_cbranch_execz .LBB0_522
	v_cmp_eq_f32_e32 vcc, 0, v96
	s_cmp_eq_u64 vcc, exec
	s_cbranch_scc1 .LBB0_522
	v_readfirstlane_b32 s66, v109
	s_add_i32 s67, s12, 64
	s_nop 1
	s_sub_i32 s66, s66, 15
	s_cmp_le_u32 s67, s66
	s_cbranch_scc1 .Lattn_nomask
	ds_read_b128 v[120:123], v116
	ds_read_b128 v[124:127], v116 offset:64
	ds_read_b128 v[128:131], v116 offset:1088
	ds_read_b128 v[132:135], v116 offset:1152
	v_add_u32_e32 v99, s56, v108
	v_add_u32_e32 v103, 64, v99
	s_waitcnt lgkmcnt(3)
	v_mfma_f32_16x16x32_bf16 v[120:123], v[120:123], v[0:3], 0
	s_waitcnt lgkmcnt(2)
	v_mfma_f32_16x16x32_bf16 v[120:123], v[124:127], v[4:7], v[120:123]
	ds_read_b128 v[124:127], v116 offset:128
	ds_read_b128 v[136:139], v116 offset:192
	s_waitcnt lgkmcnt(3)
	v_mfma_f32_16x16x32_bf16 v[128:131], v[128:131], v[0:3], 0
	s_waitcnt lgkmcnt(1)
	v_mfma_f32_16x16x32_bf16 v[120:123], v[124:127], v[8:11], v[120:123]
	ds_read_b128 v[124:127], v116 offset:1216
	ds_read_b128 v[140:143], v116 offset:1280
	ds_read_b128 v[144:147], v116 offset:8704
	ds_read_b128 v[148:151], v116 offset:8768
	v_mfma_f32_16x16x32_bf16 v[128:131], v[132:135], v[4:7], v[128:131]
	ds_read_b128 v[132:135], v116 offset:8832
	ds_read_b128 v[152:155], v116 offset:8896
	ds_read_b128 v[156:159], v116 offset:9792
	ds_read_b128 v[160:163], v116 offset:9856
	s_waitcnt lgkmcnt(8)
	v_mfma_f32_16x16x32_bf16 v[120:123], v[136:139], v[12:15], v[120:123]
	ds_read_b128 v[136:139], v116 offset:9920
	ds_read_b128 v[164:167], v116 offset:9984
	s_waitcnt lgkmcnt(9)
	v_mfma_f32_16x16x32_bf16 v[124:127], v[124:127], v[8:11], v[128:131]
	s_nop 3
	v_exp_f32_e32 v97, v120
	s_nop 0
	v_add_f32_e32 v101, 1.0, v97
	s_waitcnt lgkmcnt(7)
	v_mfma_f32_16x16x32_bf16 v[128:131], v[144:147], v[0:3], 0
	v_rcp_f32_e32 v101, v101
	s_nop 0
	v_mul_f32_e32 v97, v97, v101
	s_waitcnt lgkmcnt(6)
	v_mfma_f32_16x16x32_bf16 v[128:131], v[148:151], v[4:7], v[128:131]
	v_mov_b32_e32 v120, v97
	v_mov_b32_e32 v97, v101
	v_cmp_lt_u32_e32 vcc, v103, v111
	v_mfma_f32_16x16x32_bf16 v[124:127], v[140:143], v[12:15], v[124:127]
	v_exp_f32_e32 v140, v121
	v_exp_f32_e32 v141, v122
	v_cndmask_b32_e32 v101, 0, v120, vcc
	s_waitcnt lgkmcnt(5)
	v_mfma_f32_16x16x32_bf16 v[128:131], v[132:135], v[8:11], v[128:131]
	v_add_f32_e32 v103, 1.0, v140
	v_rcp_f32_e32 v103, v103
	v_add_u32_e32 v120, 0x41, v99
	s_waitcnt lgkmcnt(3)
	v_mfma_f32_16x16x32_bf16 v[132:135], v[156:159], v[0:3], 0
	v_cmp_lt_u32_e64 s[12:13], v120, v111
	v_add_f32_e32 v120, 1.0, v141
	v_rcp_f32_e32 v120, v120
	s_waitcnt lgkmcnt(2)
	v_mfma_f32_16x16x32_bf16 v[132:135], v[160:163], v[4:7], v[132:135]
	v_cndmask_b32_e32 v97, 1.0, v97, vcc
	v_mul_f32_e32 v140, v140, v103
	s_waitcnt lgkmcnt(1)
	v_mfma_f32_16x16x32_bf16 v[132:135], v[136:139], v[8:11], v[132:135]
	v_exp_f32_e32 v136, v123
	v_exp_f32_e32 v137, v124
	v_cndmask_b32_e64 v142, 0, v140, s[12:13]
	v_add_u32_e32 v121, 0x42, v99
	v_mul_f32_e32 v140, v141, v120
	v_cndmask_b32_e64 v103, 1.0, v103, s[12:13]
	v_cmp_lt_u32_e64 s[12:13], v121, v111
	v_add_f32_e32 v121, 1.0, v136
	s_nop 0
	v_cndmask_b32_e64 v143, 0, v140, s[12:13]
	v_add_u32_e32 v122, 0x43, v99
	v_rcp_f32_e32 v121, v121
	v_cndmask_b32_e64 v120, 1.0, v120, s[12:13]
	v_cmp_lt_u32_e64 s[12:13], v122, v111
	v_add_f32_e32 v122, 1.0, v137
	v_rcp_f32_e32 v122, v122
	v_mul_f32_e32 v136, v136, v121
	v_mfma_f32_16x16x32_bf16 v[128:131], v[152:155], v[12:15], v[128:131]
	s_nop 0
	v_mov_b32_e32 v123, v136
	v_mul_f32_e32 v136, v137, v122
	v_exp_f32_e32 v137, v125
	v_cndmask_b32_e64 v144, 0, v123, s[12:13]
	v_add_u32_e32 v123, 0x44, v99
	v_cndmask_b32_e64 v121, 1.0, v121, s[12:13]
	v_cmp_lt_u32_e64 s[12:13], v123, v111
	v_add_f32_e32 v123, 1.0, v137
	v_rcp_f32_e32 v123, v123
	v_exp_f32_e32 v138, v128
	v_exp_f32_e32 v139, v131
	v_mov_b32_e32 v124, v136
	v_mul_f32_e32 v136, v137, v123
	v_exp_f32_e32 v137, v126
	v_cndmask_b32_e64 v145, 0, v124, s[12:13]
	v_add_u32_e32 v124, 0x45, v99
	v_cndmask_b32_e64 v122, 1.0, v122, s[12:13]
	v_cmp_lt_u32_e64 s[12:13], v124, v111
	v_add_f32_e32 v124, 1.0, v137
	v_rcp_f32_e32 v124, v124
	s_waitcnt lgkmcnt(0)
	v_mfma_f32_16x16x32_bf16 v[132:135], v[164:167], v[12:15], v[132:135]
	v_mov_b32_e32 v125, v136
	v_mul_f32_e32 v136, v137, v124
	v_exp_f32_e32 v137, v127
	v_cndmask_b32_e64 v146, 0, v125, s[12:13]
	v_add_u32_e32 v125, 0x46, v99
	v_cndmask_b32_e64 v123, 1.0, v123, s[12:13]
	v_cmp_lt_u32_e64 s[12:13], v125, v111
	v_mov_b32_e32 v126, v136
	v_add_f32_e32 v125, 1.0, v137
	v_add_u32_e32 v136, 0x47, v99
	v_cndmask_b32_e64 v126, 0, v126, s[12:13]
	v_rcp_f32_e32 v125, v125
	v_cndmask_b32_e64 v124, 1.0, v124, s[12:13]
	v_cmp_lt_u32_e64 s[12:13], v136, v111
	v_add_f32_e32 v136, 1.0, v138
	v_rcp_f32_e32 v136, v136
	v_mul_f32_e32 v137, v137, v125
	s_nop 1
	v_mov_b32_e32 v127, v137
	v_mul_f32_e32 v137, v138, v136
	v_exp_f32_e32 v138, v129
	v_cndmask_b32_e64 v147, 1.0, v125, s[12:13]
	v_add_u32_e32 v125, 0x60, v99
	v_cndmask_b32_e64 v127, 0, v127, s[12:13]
	v_cmp_lt_u32_e64 s[12:13], v125, v111
	v_add_f32_e32 v125, 1.0, v138
	v_rcp_f32_e32 v125, v125
	v_mul_f32_e32 v153, v147, v124
	v_mul_f32_e32 v154, v123, v153
	v_mov_b32_e32 v128, v137
	v_mul_f32_e32 v137, v138, v125
	v_exp_f32_e32 v138, v130
	v_cndmask_b32_e64 v140, 1.0, v136, s[12:13]
	v_add_u32_e32 v136, 0x61, v99
	v_cndmask_b32_e64 v128, 0, v128, s[12:13]
	v_cmp_lt_u32_e64 s[12:13], v136, v111
	v_mov_b32_e32 v129, v137
	v_add_f32_e32 v136, 1.0, v138
	v_add_u32_e32 v137, 0x62, v99
	v_cndmask_b32_e64 v129, 0, v129, s[12:13]
	v_rcp_f32_e32 v136, v136
	v_cndmask_b32_e64 v125, 1.0, v125, s[12:13]
	v_cmp_lt_u32_e64 s[12:13], v137, v111
; #define LAS __attribute__((address_space(3)))
; __device__ __forceinline__ void attn_unit(LAS unsigned char* lds, const bf16_t* Qm, const bf16_t* Km, const bf16_t* VT, const bf16_t* GBm, bf16_t* YB, int b, int hp, int qb) {
;     ...
;             for (int c = 0; c < 2; ++c)
; #pragma unroll
;                 for (int i = 0; i < 8; ++i) {
;                     const float z = s[2 * c + (i >> 2)][i & 3];
;                     const int key = k0 + 32 * c + 8 * fq + i;
;                     const float e = __builtin_amdgcn_exp2f(-fabsf(z));
;                     const float r = __builtin_amdgcn_rcpf(1.0f + e);
;                     const bool pos = z >= 0.f, valid = key < qi;
;                     be[c][i] = valid ? (pos ? r : e * r) : 0.f;
;                     om[c][i] = valid ? (pos ? e * r : r) : 1.f;
;                 }
;             float suf[2][8], Gs[2], Tt[2];
; #pragma unroll
;             for (int c = 0; c < 2; ++c) {
;                 float run = 1.f;
; #pragma unroll
;                 for (int i = 7; i >= 0; --i) { suf[c][i] = run; run *= om[c][i]; }
;                 const float t1 = __shfl(run, (lane + 16) & 63), t2 = __shfl(run, (lane + 32) & 63), t3 = __shfl(run, (lane + 48) & 63);
;                 Gs[c] = (fq < 3 ? t1 : 1.f) * (fq < 2 ? t2 : 1.f) * (fq < 1 ? t3 : 1.f);
;                 Tt[c] = (run * t1) * (t2 * t3);
;             }
;             bf16x8 pf[2];
; #pragma unroll
;             for (int c = 0; c < 2; ++c) {
;                 const float basec = Rs * Gs[c] * (c == 0 ? Tt[1] : 1.f);
;                 float w[8];
; #pragma unroll
;                 for (int i = 0; i < 8; ++i) w[i] = be[c][i] * (suf[c][i] * basec);
;                 u32x4 pw; pw.x = cvt_pk_bf16(w[0], w[1]); pw.y = cvt_pk_bf16(w[2], w[3]); pw.z = cvt_pk_bf16(w[4], w[5]); pw.w = cvt_pk_bf16(w[6], w[7]);
;                 pf[c] = __builtin_bit_cast(bf16x8, pw);
;             }
;             Rs *= Tt[0] * Tt[1];
; #pragma unroll
;             for (int db = 0; db < 8; ++db)
; #pragma unroll
;                 for (int c = 0; c < 2; ++c) {
;                     const bf16x8 a = *(const LAS bf16x8*)(VL + (db * 16 + fr) * 144 + (32 * c + 8 * fq) * 2);
;                     o[db] = __builtin_amdgcn_mfma_f32_16x16x32_bf16(a, pf[c], o[db], 0, 0, 0);
;                 }
	v_add_f32_e32 v137, 1.0, v139
	v_rcp_f32_e32 v137, v137
	v_mul_f32_e32 v138, v138, v136
	v_mul_f32_e32 v155, v122, v154
	v_mul_f32_e32 v156, v121, v155
	v_mov_b32_e32 v130, v138
	v_mul_f32_e32 v138, v139, v137
	v_exp_f32_e32 v139, v132
	v_cndmask_b32_e64 v141, 1.0, v136, s[12:13]
	v_add_u32_e32 v136, 0x63, v99
	v_cndmask_b32_e64 v130, 0, v130, s[12:13]
	v_cmp_lt_u32_e64 s[12:13], v136, v111
	v_add_f32_e32 v136, 1.0, v139
	v_rcp_f32_e32 v136, v136
	v_mul_f32_e32 v157, v120, v156
	v_mul_f32_e32 v103, v103, v157
	v_mov_b32_e32 v131, v138
	v_mul_f32_e32 v138, v139, v136
	v_exp_f32_e32 v139, v133
	v_cndmask_b32_e64 v148, 1.0, v137, s[12:13]
	v_add_u32_e32 v137, 0x64, v99
	v_cndmask_b32_e64 v131, 0, v131, s[12:13]
	v_cmp_lt_u32_e64 s[12:13], v137, v111
	v_add_f32_e32 v137, 1.0, v139
	v_rcp_f32_e32 v137, v137
	s_nop 1
	v_mov_b32_e32 v132, v138
	v_mul_f32_e32 v138, v139, v137
	v_exp_f32_e32 v139, v134
	v_cndmask_b32_e64 v149, 1.0, v136, s[12:13]
	v_add_u32_e32 v136, 0x65, v99
	v_cndmask_b32_e64 v132, 0, v132, s[12:13]
	v_cmp_lt_u32_e64 s[12:13], v136, v111
	v_add_f32_e32 v136, 1.0, v139
	v_rcp_f32_e32 v136, v136
	s_nop 1
	v_mov_b32_e32 v133, v138
	v_mul_f32_e32 v138, v139, v136
	v_exp_f32_e32 v139, v135
	v_cndmask_b32_e64 v150, 1.0, v137, s[12:13]
	v_add_u32_e32 v137, 0x66, v99
	v_cndmask_b32_e64 v133, 0, v133, s[12:13]
	v_cmp_lt_u32_e64 s[12:13], v137, v111
	v_add_f32_e32 v137, 1.0, v139
	v_rcp_f32_e32 v151, v137
	v_add_u32_e32 v99, 0x67, v99
	v_mul_f32_e32 v139, v139, v151
	v_cndmask_b32_e64 v134, 0, v138, s[12:13]
	v_cndmask_b32_e64 v152, 1.0, v136, s[12:13]
	v_cmp_lt_u32_e64 s[12:13], v99, v111
	v_mul_f32_e32 v136, v97, v103
	s_nop 0
	v_cndmask_b32_e64 v99, 0, v139, s[12:13]
	v_or_b32_e32 v135, v105, v107
	v_lshlrev_b32_e32 v135, 2, v135
	v_cndmask_b32_e64 v151, 1.0, v151, s[12:13]
	v_xor_b32_e32 v135, 0x80, v135
	v_mul_f32_e32 v152, v151, v152
	ds_bpermute_b32 v137, v135, v136
	ds_bpermute_b32 v138, v118, v136
	v_mul_f32_e32 v150, v150, v152
	v_mul_f32_e32 v149, v149, v150
	v_mul_f32_e32 v148, v148, v149
	v_mul_f32_e32 v158, v141, v148
	v_mul_f32_e32 v159, v125, v158
	ds_bpermute_b32 v139, v119, v136
	s_waitcnt lgkmcnt(2)
	v_cndmask_b32_e64 v97, 1.0, v137, s[10:11]
	s_waitcnt lgkmcnt(1)
	v_cndmask_b32_e64 v120, v138, 1.0, s[0:1]
	v_mul_f32_e32 v121, v140, v159
	v_mul_f32_e32 v97, v120, v97
	ds_bpermute_b32 v120, v135, v121
	ds_bpermute_b32 v123, v118, v121
	ds_bpermute_b32 v122, v119, v121
	s_waitcnt lgkmcnt(3)
	v_cndmask_b32_e64 v124, 1.0, v139, s[4:5]
	v_mul_f32_e32 v124, v97, v124
	s_waitcnt lgkmcnt(2)
	v_cndmask_b32_e64 v97, 1.0, v120, s[10:11]
	s_waitcnt lgkmcnt(1)
	v_cndmask_b32_e64 v125, v123, 1.0, s[0:1]
	v_mul_f32_e32 v97, v125, v97
	s_waitcnt lgkmcnt(0)
	v_cndmask_b32_e64 v125, 1.0, v122, s[4:5]
	v_pk_mul_f32 v[120:121], v[120:121], v[122:123]
	v_mul_f32_e32 v135, v97, v125
	v_mov_b32_e32 v97, v120
	v_mov_b32_e32 v125, v121
	v_pk_mul_f32 v[140:141], v[96:97], v[124:125]
	s_nop 0
	v_mul_f32_e32 v97, v140, v141
	v_mul_f32_e32 v120, v156, v97
	v_mul_f32_e32 v121, v143, v120
	v_mul_f32_e32 v120, v155, v97
	v_mul_f32_e32 v122, v144, v120
	v_mul_f32_e32 v120, v154, v97
	v_mul_f32_e32 v103, v103, v97
	v_mul_f32_e32 v123, v145, v120
	v_mul_f32_e32 v120, v153, v97
	v_mul_f32_e32 v101, v101, v103
	v_mul_f32_e32 v103, v157, v97
	v_mul_f32_e32 v124, v146, v120
	v_mul_f32_e32 v120, v147, v97
	v_mul_f32_e32 v97, v127, v97
	v_mul_f32_e32 v103, v142, v103
	v_mul_f32_e32 v125, v126, v120
	v_cvt_pk_bf16_f32 v120, v101, v103
	v_cvt_pk_bf16_f32 v121, v121, v122
	v_cvt_pk_bf16_f32 v122, v123, v124
	v_cvt_pk_bf16_f32 v123, v125, v97
	v_mul_f32_e32 v97, v96, v135
	v_mul_f32_e32 v124, v97, v148
	v_mul_f32_e32 v125, v130, v124
	v_mul_f32_e32 v124, v97, v149
	v_mul_f32_e32 v126, v131, v124
	v_mul_f32_e32 v124, v97, v150
	v_mul_f32_e32 v101, v97, v159
	v_mul_f32_e32 v127, v132, v124
	v_mul_f32_e32 v124, v97, v152
	v_mul_f32_e32 v101, v128, v101
	v_mul_f32_e32 v103, v97, v158
	v_mul_f32_e32 v128, v133, v124
	v_mul_f32_e32 v124, v151, v97
	v_mul_f32_e32 v103, v129, v103
	v_mul_f32_e32 v129, v134, v124
	v_mul_f32_e32 v97, v99, v97
	v_cvt_pk_bf16_f32 v124, v101, v103
	v_cvt_pk_bf16_f32 v125, v125, v126
	v_cvt_pk_bf16_f32 v126, v127, v128
	v_cvt_pk_bf16_f32 v127, v129, v97
	ds_read_b128 v[128:131], v117 offset:17408
	ds_read_b128 v[132:135], v117 offset:17472
	s_waitcnt lgkmcnt(1)
	v_mfma_f32_16x16x32_bf16 v[60:63], v[128:131], v[120:123], v[60:63]
	ds_read_b128 v[128:131], v117 offset:19712
	s_waitcnt lgkmcnt(1)
	v_mfma_f32_16x16x32_bf16 v[60:63], v[132:135], v[124:127], v[60:63]
	ds_read_b128 v[132:135], v117 offset:19776
	s_waitcnt lgkmcnt(1)
	v_mfma_f32_16x16x32_bf16 v[72:75], v[128:131], v[120:123], v[72:75]
	ds_read_b128 v[128:131], v117 offset:22016
	s_waitcnt lgkmcnt(1)
	v_mfma_f32_16x16x32_bf16 v[72:75], v[132:135], v[124:127], v[72:75]
	ds_read_b128 v[132:135], v117 offset:22080
	s_waitcnt lgkmcnt(1)
	v_mfma_f32_16x16x32_bf16 v[56:59], v[128:131], v[120:123], v[56:59]
	ds_read_b128 v[128:131], v117 offset:24320
	s_waitcnt lgkmcnt(1)
	v_mfma_f32_16x16x32_bf16 v[56:59], v[132:135], v[124:127], v[56:59]
	ds_read_b128 v[132:135], v117 offset:24384
	s_waitcnt lgkmcnt(1)
	v_mfma_f32_16x16x32_bf16 v[44:47], v[128:131], v[120:123], v[44:47]
	ds_read_b128 v[128:131], v117 offset:26624
	s_waitcnt lgkmcnt(1)
	v_mfma_f32_16x16x32_bf16 v[44:47], v[132:135], v[124:127], v[44:47]
	ds_read_b128 v[132:135], v117 offset:26688
	s_waitcnt lgkmcnt(1)
	v_mfma_f32_16x16x32_bf16 v[32:35], v[128:131], v[120:123], v[32:35]
	ds_read_b128 v[128:131], v117 offset:28928
	s_waitcnt lgkmcnt(1)
	v_mfma_f32_16x16x32_bf16 v[32:35], v[132:135], v[124:127], v[32:35]
	ds_read_b128 v[132:135], v117 offset:28992
	s_waitcnt lgkmcnt(1)
	v_mfma_f32_16x16x32_bf16 v[24:27], v[128:131], v[120:123], v[24:27]
	ds_read_b128 v[128:131], v117 offset:31232
	s_waitcnt lgkmcnt(1)
	v_mfma_f32_16x16x32_bf16 v[24:27], v[132:135], v[124:127], v[24:27]
	ds_read_b128 v[132:135], v117 offset:31296
	s_waitcnt lgkmcnt(1)
	v_mfma_f32_16x16x32_bf16 v[20:23], v[128:131], v[120:123], v[20:23]
	ds_read_b128 v[128:131], v117 offset:33536
	s_waitcnt lgkmcnt(1)
	v_mfma_f32_16x16x32_bf16 v[20:23], v[132:135], v[124:127], v[20:23]
	ds_read_b128 v[132:135], v117 offset:33600
	s_waitcnt lgkmcnt(1)
	v_mfma_f32_16x16x32_bf16 v[16:19], v[128:131], v[120:123], v[16:19]
	v_mul_f32_e64 v120, v136, v138
	v_mul_f32_e64 v121, v137, v139
	v_mul_f32_e32 v97, v120, v121
	s_waitcnt lgkmcnt(0)
	v_mfma_f32_16x16x32_bf16 v[16:19], v[132:135], v[124:127], v[16:19]
	v_mul_f32_e32 v97, v97, v141
	v_mul_f32_e32 v96, v96, v97
	s_branch .LBB0_522
; #define LAS __attribute__((address_space(3)))
; __device__ __forceinline__ void attn_unit(LAS unsigned char* lds, const bf16_t* Qm, const bf16_t* Km, const bf16_t* VT, const bf16_t* GBm, bf16_t* YB, int b, int hp, int qb) {
;     ...
;         if (k0 < qw + 15 && !__all(Rs == 0.f)) {
;             f32x4 s[4];
; #pragma unroll
;             for (int rb = 0; rb < 4; ++rb) {
;                 const int c = rb >> 1, e = rb & 1;
;                 const int kl = 32 * c + (fr >> 2) * 8 + e * 4 + (fr & 3);
;                 s[rb] = (f32x4){0.f, 0.f, 0.f, 0.f};
; #pragma unroll
;                 for (int ks = 0; ks < 4; ++ks) {
;                     const bf16x8 a = *(const LAS bf16x8*)(KL + kl * 272 + (ks * 32 + fq * 8) * 2);
;                     s[rb] = __builtin_amdgcn_mfma_f32_16x16x32_bf16(a, qf[ks], s[rb], 0, 0, 0);
;                 }
;             }
;             const int qi = qw + fr;
;             float be[2][8], om[2][8];
; #pragma unroll
;             for (int c = 0; c < 2; ++c)
; #pragma unroll
;                 for (int i = 0; i < 8; ++i) {
;                     const float z = s[2 * c + (i >> 2)][i & 3];
;                     const int key = k0 + 32 * c + 8 * fq + i;
;                     const float e = __builtin_amdgcn_exp2f(-fabsf(z));
;                     const float r = __builtin_amdgcn_rcpf(1.0f + e);
;                     const bool pos = z >= 0.f, valid = key < qi;
;                     be[c][i] = valid ? (pos ? r : e * r) : 0.f;
;                     om[c][i] = valid ? (pos ? e * r : r) : 1.f;
;                 }
;             float suf[2][8], Gs[2], Tt[2];
; #pragma unroll
;             for (int c = 0; c < 2; ++c) {
;                 float run = 1.f;
; #pragma unroll
;                 for (int i = 7; i >= 0; --i) { suf[c][i] = run; run *= om[c][i]; }
;                 const float t1 = __shfl(run, (lane + 16) & 63), t2 = __shfl(run, (lane + 32) & 63), t3 = __shfl(run, (lane + 48) & 63);
.Lattn_nomask:
	ds_read_b128 v[120:123], v116
	ds_read_b128 v[124:127], v116 offset:64
	ds_read_b128 v[128:131], v116 offset:1088
	ds_read_b128 v[132:135], v116 offset:1152
	v_add_u32_e32 v99, s56, v108
	s_waitcnt lgkmcnt(3)
	v_mfma_f32_16x16x32_bf16 v[120:123], v[120:123], v[0:3], 0
	s_waitcnt lgkmcnt(2)
	v_mfma_f32_16x16x32_bf16 v[120:123], v[124:127], v[4:7], v[120:123]
	ds_read_b128 v[124:127], v116 offset:128
	ds_read_b128 v[136:139], v116 offset:192
	s_waitcnt lgkmcnt(3)
	v_mfma_f32_16x16x32_bf16 v[128:131], v[128:131], v[0:3], 0
	s_waitcnt lgkmcnt(1)
	v_mfma_f32_16x16x32_bf16 v[120:123], v[124:127], v[8:11], v[120:123]
	ds_read_b128 v[124:127], v116 offset:1216
	ds_read_b128 v[140:143], v116 offset:1280
	ds_read_b128 v[144:147], v116 offset:8704
	ds_read_b128 v[148:151], v116 offset:8768
	v_mfma_f32_16x16x32_bf16 v[128:131], v[132:135], v[4:7], v[128:131]
	ds_read_b128 v[132:135], v116 offset:8832
	ds_read_b128 v[152:155], v116 offset:8896
	ds_read_b128 v[156:159], v116 offset:9792
	ds_read_b128 v[160:163], v116 offset:9856
	s_waitcnt lgkmcnt(8)
	v_mfma_f32_16x16x32_bf16 v[120:123], v[136:139], v[12:15], v[120:123]
	ds_read_b128 v[136:139], v116 offset:9920
	ds_read_b128 v[164:167], v116 offset:9984
	s_waitcnt lgkmcnt(9)
	v_mfma_f32_16x16x32_bf16 v[124:127], v[124:127], v[8:11], v[128:131]
	s_nop 3
	v_exp_f32_e32 v97, v120
	s_nop 0
	v_add_f32_e32 v101, 1.0, v97
	s_waitcnt lgkmcnt(7)
	v_mfma_f32_16x16x32_bf16 v[128:131], v[144:147], v[0:3], 0
	v_rcp_f32_e32 v101, v101
	s_nop 0
	v_mul_f32_e32 v97, v97, v101
	s_waitcnt lgkmcnt(6)
	v_mfma_f32_16x16x32_bf16 v[128:131], v[148:151], v[4:7], v[128:131]
	v_mov_b32_e32 v120, v97
	v_mov_b32_e32 v97, v101
	v_mfma_f32_16x16x32_bf16 v[124:127], v[140:143], v[12:15], v[124:127]
	v_exp_f32_e32 v140, v121
	v_exp_f32_e32 v141, v122
	v_mov_b32_e32 v101, v120
	s_waitcnt lgkmcnt(5)
	v_mfma_f32_16x16x32_bf16 v[128:131], v[132:135], v[8:11], v[128:131]
	v_add_f32_e32 v103, 1.0, v140
	v_rcp_f32_e32 v103, v103
	s_waitcnt lgkmcnt(3)
	v_mfma_f32_16x16x32_bf16 v[132:135], v[156:159], v[0:3], 0
	v_add_f32_e32 v120, 1.0, v141
	v_rcp_f32_e32 v120, v120
	s_waitcnt lgkmcnt(2)
	v_mfma_f32_16x16x32_bf16 v[132:135], v[160:163], v[4:7], v[132:135]
	v_mul_f32_e32 v140, v140, v103
	s_waitcnt lgkmcnt(1)
	v_mfma_f32_16x16x32_bf16 v[132:135], v[136:139], v[8:11], v[132:135]
	v_exp_f32_e32 v136, v123
	v_exp_f32_e32 v137, v124
	v_mov_b32_e32 v142, v140
	v_mul_f32_e32 v140, v141, v120
	v_add_f32_e32 v121, 1.0, v136
	v_mov_b32_e32 v143, v140
	v_rcp_f32_e32 v121, v121
	v_add_f32_e32 v122, 1.0, v137
	v_rcp_f32_e32 v122, v122
	v_mul_f32_e32 v136, v136, v121
	v_mfma_f32_16x16x32_bf16 v[128:131], v[152:155], v[12:15], v[128:131]
	s_nop 0
	v_mov_b32_e32 v123, v136
	v_mul_f32_e32 v136, v137, v122
	v_exp_f32_e32 v137, v125
	v_mov_b32_e32 v144, v123
	v_add_f32_e32 v123, 1.0, v137
	v_rcp_f32_e32 v123, v123
	s_nop 0
	v_exp_f32_e32 v138, v128
	v_exp_f32_e32 v139, v131
	v_mov_b32_e32 v124, v136
	v_mul_f32_e32 v136, v137, v123
	v_exp_f32_e32 v137, v126
	v_mov_b32_e32 v145, v124
	v_add_f32_e32 v124, 1.0, v137
	v_rcp_f32_e32 v124, v124
	s_waitcnt lgkmcnt(0)
	v_mfma_f32_16x16x32_bf16 v[132:135], v[164:167], v[12:15], v[132:135]
	v_mov_b32_e32 v125, v136
	v_mul_f32_e32 v136, v137, v124
	v_exp_f32_e32 v137, v127
	v_mov_b32_e32 v146, v125
	v_mov_b32_e32 v126, v136
	v_add_f32_e32 v125, 1.0, v137
	v_rcp_f32_e32 v125, v125
	v_add_f32_e32 v136, 1.0, v138
	v_rcp_f32_e32 v136, v136
	v_mul_f32_e32 v137, v137, v125
	s_nop 1
	v_mov_b32_e32 v127, v137
	v_mul_f32_e32 v137, v138, v136
	v_exp_f32_e32 v138, v129
	v_mov_b32_e32 v147, v125
	v_add_f32_e32 v125, 1.0, v138
	v_rcp_f32_e32 v125, v125
	v_mul_f32_e32 v153, v147, v124
	v_mul_f32_e32 v154, v123, v153
	v_mov_b32_e32 v128, v137
	v_mul_f32_e32 v137, v138, v125
	v_exp_f32_e32 v138, v130
	v_mov_b32_e32 v140, v136
	v_mov_b32_e32 v129, v137
	v_add_f32_e32 v136, 1.0, v138
	v_rcp_f32_e32 v136, v136
	v_add_f32_e32 v137, 1.0, v139
	v_rcp_f32_e32 v137, v137
	v_mul_f32_e32 v138, v138, v136
	v_mul_f32_e32 v155, v122, v154
	v_mul_f32_e32 v156, v121, v155
	v_mov_b32_e32 v130, v138
	v_mul_f32_e32 v138, v139, v137
	v_exp_f32_e32 v139, v132
	v_mov_b32_e32 v141, v136
	v_add_f32_e32 v136, 1.0, v139
	v_rcp_f32_e32 v136, v136
	v_mul_f32_e32 v157, v120, v156
	v_mul_f32_e32 v103, v103, v157
	v_mov_b32_e32 v131, v138
	v_mul_f32_e32 v138, v139, v136
	v_exp_f32_e32 v139, v133
	v_mov_b32_e32 v148, v137
	v_add_f32_e32 v137, 1.0, v139
	v_rcp_f32_e32 v137, v137
	s_nop 1
	v_mov_b32_e32 v132, v138
	v_mul_f32_e32 v138, v139, v137
	v_exp_f32_e32 v139, v134
	v_mov_b32_e32 v149, v136
	v_add_f32_e32 v136, 1.0, v139
	v_rcp_f32_e32 v136, v136
	s_nop 1
	v_mov_b32_e32 v133, v138
	v_mul_f32_e32 v138, v139, v136
	v_exp_f32_e32 v139, v135
	v_mov_b32_e32 v150, v137
	v_add_f32_e32 v137, 1.0, v139
	v_rcp_f32_e32 v151, v137
	s_nop 0
	v_mul_f32_e32 v139, v139, v151
	v_mov_b32_e32 v134, v138
	v_mov_b32_e32 v152, v136
	v_mul_f32_e32 v136, v97, v103
	v_mov_b32_e32 v99, v139
	v_or_b32_e32 v135, v105, v107
	v_lshlrev_b32_e32 v135, 2, v135
	v_xor_b32_e32 v135, 0x80, v135
	v_mul_f32_e32 v152, v151, v152
	ds_bpermute_b32 v137, v135, v136
	ds_bpermute_b32 v138, v118, v136
	v_mul_f32_e32 v150, v150, v152
	v_mul_f32_e32 v149, v149, v150
	v_mul_f32_e32 v148, v148, v149
	v_mul_f32_e32 v158, v141, v148
	v_mul_f32_e32 v159, v125, v158
	ds_bpermute_b32 v139, v119, v136
	s_waitcnt lgkmcnt(2)
; #define LAS __attribute__((address_space(3)))
; __device__ __forceinline__ unsigned cvt_pk_bf16(float lo, float hi) { unsigned r; asm volatile("v_cvt_pk_bf16_f32 %0, %1, %2" : "=v"(r) : "v"(lo), "v"(hi)); return r; }
; __device__ __forceinline__ void attn_unit(LAS unsigned char* lds, const bf16_t* Qm, const bf16_t* Km, const bf16_t* VT, const bf16_t* GBm, bf16_t* YB, int b, int hp, int qb) {
;     ...
;             float suf[2][8], Gs[2], Tt[2];
; #pragma unroll
;             for (int c = 0; c < 2; ++c) {
;                 float run = 1.f;
; #pragma unroll
;                 for (int i = 7; i >= 0; --i) { suf[c][i] = run; run *= om[c][i]; }
;                 const float t1 = __shfl(run, (lane + 16) & 63), t2 = __shfl(run, (lane + 32) & 63), t3 = __shfl(run, (lane + 48) & 63);
;                 Gs[c] = (fq < 3 ? t1 : 1.f) * (fq < 2 ? t2 : 1.f) * (fq < 1 ? t3 : 1.f);
;                 Tt[c] = (run * t1) * (t2 * t3);
;             }
;             bf16x8 pf[2];
; #pragma unroll
;             for (int c = 0; c < 2; ++c) {
;                 const float basec = Rs * Gs[c] * (c == 0 ? Tt[1] : 1.f);
;                 float w[8];
; #pragma unroll
;                 for (int i = 0; i < 8; ++i) w[i] = be[c][i] * (suf[c][i] * basec);
;                 u32x4 pw; pw.x = cvt_pk_bf16(w[0], w[1]); pw.y = cvt_pk_bf16(w[2], w[3]); pw.z = cvt_pk_bf16(w[4], w[5]); pw.w = cvt_pk_bf16(w[6], w[7]);
;                 pf[c] = __builtin_bit_cast(bf16x8, pw);
;             }
;             Rs *= Tt[0] * Tt[1];
; #pragma unroll
;             for (int db = 0; db < 8; ++db)
; #pragma unroll
;                 for (int c = 0; c < 2; ++c) {
;                     const bf16x8 a = *(const LAS bf16x8*)(VL + (db * 16 + fr) * 144 + (32 * c + 8 * fq) * 2);
;                     o[db] = __builtin_amdgcn_mfma_f32_16x16x32_bf16(a, pf[c], o[db], 0, 0, 0);
;                 }
	v_cndmask_b32_e64 v97, 1.0, v137, s[10:11]
	s_waitcnt lgkmcnt(1)
	v_cndmask_b32_e64 v120, v138, 1.0, s[0:1]
	v_mul_f32_e32 v121, v140, v159
	v_mul_f32_e32 v97, v120, v97
	ds_bpermute_b32 v120, v135, v121
	ds_bpermute_b32 v123, v118, v121
	ds_bpermute_b32 v122, v119, v121
	s_waitcnt lgkmcnt(3)
	v_cndmask_b32_e64 v124, 1.0, v139, s[4:5]
	v_mul_f32_e32 v124, v97, v124
	s_waitcnt lgkmcnt(2)
	v_cndmask_b32_e64 v97, 1.0, v120, s[10:11]
	s_waitcnt lgkmcnt(1)
	v_cndmask_b32_e64 v125, v123, 1.0, s[0:1]
	v_mul_f32_e32 v97, v125, v97
	s_waitcnt lgkmcnt(0)
	v_cndmask_b32_e64 v125, 1.0, v122, s[4:5]
	v_pk_mul_f32 v[120:121], v[120:121], v[122:123]
	v_mul_f32_e32 v135, v97, v125
	v_mov_b32_e32 v97, v120
	v_mov_b32_e32 v125, v121
	v_pk_mul_f32 v[140:141], v[96:97], v[124:125]
	s_nop 0
	v_mul_f32_e32 v97, v140, v141
	v_mul_f32_e32 v120, v156, v97
	v_mul_f32_e32 v121, v143, v120
	v_mul_f32_e32 v120, v155, v97
	v_mul_f32_e32 v122, v144, v120
	v_mul_f32_e32 v120, v154, v97
	v_mul_f32_e32 v103, v103, v97
	v_mul_f32_e32 v123, v145, v120
	v_mul_f32_e32 v120, v153, v97
	v_mul_f32_e32 v101, v101, v103
	v_mul_f32_e32 v103, v157, v97
	v_mul_f32_e32 v124, v146, v120
	v_mul_f32_e32 v120, v147, v97
	v_mul_f32_e32 v97, v127, v97
	v_mul_f32_e32 v103, v142, v103
	v_mul_f32_e32 v125, v126, v120
	v_cvt_pk_bf16_f32 v120, v101, v103
	v_cvt_pk_bf16_f32 v121, v121, v122
	v_cvt_pk_bf16_f32 v122, v123, v124
	v_cvt_pk_bf16_f32 v123, v125, v97
	v_mul_f32_e32 v97, v96, v135
	v_mul_f32_e32 v124, v97, v148
	v_mul_f32_e32 v125, v130, v124
	v_mul_f32_e32 v124, v97, v149
	v_mul_f32_e32 v126, v131, v124
	v_mul_f32_e32 v124, v97, v150
	v_mul_f32_e32 v101, v97, v159
	v_mul_f32_e32 v127, v132, v124
	v_mul_f32_e32 v124, v97, v152
	v_mul_f32_e32 v101, v128, v101
	v_mul_f32_e32 v103, v97, v158
	v_mul_f32_e32 v128, v133, v124
	v_mul_f32_e32 v124, v151, v97
	v_mul_f32_e32 v103, v129, v103
	v_mul_f32_e32 v129, v134, v124
	v_mul_f32_e32 v97, v99, v97
	v_cvt_pk_bf16_f32 v124, v101, v103
	v_cvt_pk_bf16_f32 v125, v125, v126
	v_cvt_pk_bf16_f32 v126, v127, v128
	v_cvt_pk_bf16_f32 v127, v129, v97
	ds_read_b128 v[128:131], v117 offset:17408
	ds_read_b128 v[132:135], v117 offset:17472
	s_waitcnt lgkmcnt(1)
	v_mfma_f32_16x16x32_bf16 v[60:63], v[128:131], v[120:123], v[60:63]
	ds_read_b128 v[128:131], v117 offset:19712
	s_waitcnt lgkmcnt(1)
	v_mfma_f32_16x16x32_bf16 v[60:63], v[132:135], v[124:127], v[60:63]
	ds_read_b128 v[132:135], v117 offset:19776
	s_waitcnt lgkmcnt(1)
	v_mfma_f32_16x16x32_bf16 v[72:75], v[128:131], v[120:123], v[72:75]
	ds_read_b128 v[128:131], v117 offset:22016
	s_waitcnt lgkmcnt(1)
	v_mfma_f32_16x16x32_bf16 v[72:75], v[132:135], v[124:127], v[72:75]
	ds_read_b128 v[132:135], v117 offset:22080
	s_waitcnt lgkmcnt(1)
	v_mfma_f32_16x16x32_bf16 v[56:59], v[128:131], v[120:123], v[56:59]
	ds_read_b128 v[128:131], v117 offset:24320
	s_waitcnt lgkmcnt(1)
	v_mfma_f32_16x16x32_bf16 v[56:59], v[132:135], v[124:127], v[56:59]
	ds_read_b128 v[132:135], v117 offset:24384
	s_waitcnt lgkmcnt(1)
	v_mfma_f32_16x16x32_bf16 v[44:47], v[128:131], v[120:123], v[44:47]
	ds_read_b128 v[128:131], v117 offset:26624
	s_waitcnt lgkmcnt(1)
	v_mfma_f32_16x16x32_bf16 v[44:47], v[132:135], v[124:127], v[44:47]
	ds_read_b128 v[132:135], v117 offset:26688
	s_waitcnt lgkmcnt(1)
	v_mfma_f32_16x16x32_bf16 v[32:35], v[128:131], v[120:123], v[32:35]
	ds_read_b128 v[128:131], v117 offset:28928
	s_waitcnt lgkmcnt(1)
	v_mfma_f32_16x16x32_bf16 v[32:35], v[132:135], v[124:127], v[32:35]
	ds_read_b128 v[132:135], v117 offset:28992
	s_waitcnt lgkmcnt(1)
	v_mfma_f32_16x16x32_bf16 v[24:27], v[128:131], v[120:123], v[24:27]
	ds_read_b128 v[128:131], v117 offset:31232
	s_waitcnt lgkmcnt(1)
	v_mfma_f32_16x16x32_bf16 v[24:27], v[132:135], v[124:127], v[24:27]
	ds_read_b128 v[132:135], v117 offset:31296
	s_waitcnt lgkmcnt(1)
	v_mfma_f32_16x16x32_bf16 v[20:23], v[128:131], v[120:123], v[20:23]
	ds_read_b128 v[128:131], v117 offset:33536
	s_waitcnt lgkmcnt(1)
	v_mfma_f32_16x16x32_bf16 v[20:23], v[132:135], v[124:127], v[20:23]
	ds_read_b128 v[132:135], v117 offset:33600
	s_waitcnt lgkmcnt(1)
	v_mfma_f32_16x16x32_bf16 v[16:19], v[128:131], v[120:123], v[16:19]
	v_mul_f32_e64 v120, v136, v138
	v_mul_f32_e64 v121, v137, v139
	v_mul_f32_e32 v97, v120, v121
	s_waitcnt lgkmcnt(0)
	v_mfma_f32_16x16x32_bf16 v[16:19], v[132:135], v[124:127], v[16:19]
	v_mul_f32_e32 v97, v97, v141
	v_mul_f32_e32 v96, v96, v97
